# v5 + NRB=2 sample-row mini GEMMs (P5 x2, P6, P11): 12 operand loads issued together with one wait instead of hipcc load/wait ladder
# speedup vs baseline: 1.0024x; 1.0012x over previous
;     ...
;         for (int s0 = 0; s0 < nsw; s0 += KS) {
;             bf16x8 a[KS][NRB], b[KS], c[KS];
; #pragma unroll
;             for (int s = 0; s < KS; ++s) { const bool on = s0 + s < nsw; const int ko = (s0 + s) * 32;
;                 b[s] = on ? *(const bf16x8*)(bp + ko) : (bf16x8){0, 0, 0, 0, 0, 0, 0, 0}; if (TWO) c[s] = on ? *(const bf16x8*)(bp + (size_t)128 * K + ko) : (bf16x8){0, 0, 0, 0, 0, 0, 0, 0};
; #pragma unroll
;                 for (int r = 0; r < NRB; ++r) a[s][r] = on ? *(const bf16x8*)(ap + (size_t)(16 * r) * K + ko) : (bf16x8){0, 0, 0, 0, 0, 0, 0, 0}; }
; #pragma unroll
;             for (int s = 0; s < KS; ++s)
; #pragma unroll
;                 for (int r = 0; r < NRB; ++r) { acc0[r] = __builtin_amdgcn_mfma_f32_16x16x32_bf16(b[s], a[s][r], acc0[r], 0, 0, 0); if (TWO) acc1[r] = __builtin_amdgcn_mfma_f32_16x16x32_bf16(c[s], a[s][r], acc1[r], 0, 0, 0); }
;         }
;         f32x4 t0 = (f32x4){0.f, 0.f, 0.f, 0.f}, t1 = (f32x4){0.f, 0.f, 0.f, 0.f};
; #pragma unroll
;         for (int r = 0; r < NRB; ++r) red[(wave * NRB + r) * 64 + lane] = acc0[r];
;         __syncthreads();
;         if (wave < NRB) {
; #pragma unroll
;             for (int s = 0; s < 8; ++s) t0 += red[(s * NRB + wave) * 64 + lane]; }
.LBB0_723:
	s_ashr_i32 s0, s5, 31
	s_lshr_b32 s1, s0, 26
	s_add_i32 s1, s5, s1
	s_ashr_i32 s1, s1, 6
	s_lshr_b32 s6, s1, 30
	s_lshr_b32 s0, s0, 24
	s_add_i32 s6, s1, s6
	s_add_i32 s0, s5, s0
	s_and_b32 s6, s6, 0x7fffffc
	s_ashr_i32 s0, s0, 8
	s_sub_i32 s6, s1, s6
	s_lshl_b32 s0, s0, 7
	s_lshl_b32 s6, s6, 5
	s_lshl_b32 s7, s1, 10
	s_add_i32 s6, s0, s6
	s_sub_i32 s0, s4, s7
	v_add_u32_e32 v12, s0, v152
	v_ashrrev_i32_e32 v13, 31, v12
	v_lshlrev_b64 v[12:13], 11, v[12:13]
	s_addk_i32 s6, 0x4000
	v_lshl_add_u64 v[44:45], v[10:11], 0, v[12:13]
	v_or_b32_e32 v20, s6, v152
	v_ashrrev_i32_e32 v21, 31, v20
	v_lshlrev_b64 v[20:21], 11, v[20:21]
	v_lshl_add_u64 v[48:49], v[8:9], 0, v[20:21]
	v_add_co_u32_e64 v50, s[0:1], s16, v48
	s_nop 1
	v_addc_co_u32_e64 v51, s[0:1], 0, v49, s[0:1]
	global_load_dwordx4 v[52:55], v[44:45], off
	global_load_dwordx4 v[56:59], v[48:49], off
	global_load_dwordx4 v[60:63], v[50:51], off
	global_load_dwordx4 v[64:67], v[44:45], off offset:64
	global_load_dwordx4 v[68:71], v[48:49], off offset:64
	global_load_dwordx4 v[72:75], v[44:45], off offset:128
	global_load_dwordx4 v[76:79], v[50:51], off offset:64
	global_load_dwordx4 v[80:83], v[48:49], off offset:128
	global_load_dwordx4 v[84:87], v[44:45], off offset:192
	global_load_dwordx4 v[88:91], v[50:51], off offset:128
	global_load_dwordx4 v[92:95], v[48:49], off offset:192
	global_load_dwordx4 v[96:99], v[50:51], off offset:192
	s_waitcnt vmcnt(0)
	v_mfma_f32_16x16x32_bf16 v[20:23], v[52:55], v[56:59], 0
	v_mfma_f32_16x16x32_bf16 v[12:15], v[52:55], v[60:63], 0
	v_mfma_f32_16x16x32_bf16 v[20:23], v[64:67], v[68:71], v[20:23]
	v_mfma_f32_16x16x32_bf16 v[12:15], v[64:67], v[76:79], v[12:15]
	v_mfma_f32_16x16x32_bf16 v[20:23], v[72:75], v[80:83], v[20:23]
	v_mfma_f32_16x16x32_bf16 v[12:15], v[72:75], v[88:91], v[12:15]
	v_mfma_f32_16x16x32_bf16 v[20:23], v[84:87], v[92:95], v[20:23]
	v_mfma_f32_16x16x32_bf16 v[12:15], v[84:87], v[96:99], v[12:15]
	v_mfma_f32_16x16x32_bf16 v[20:23], v[0:3], v[0:3], v[20:23]
	v_mfma_f32_16x16x32_bf16 v[12:15], v[0:3], v[0:3], v[12:15]
	v_mfma_f32_16x16x32_bf16 v[20:23], v[0:3], v[0:3], v[20:23]
	v_mfma_f32_16x16x32_bf16 v[12:15], v[0:3], v[0:3], v[12:15]
	v_mfma_f32_16x16x32_bf16 v[20:23], v[0:3], v[0:3], v[20:23]
	v_mfma_f32_16x16x32_bf16 v[12:15], v[0:3], v[0:3], v[12:15]
	v_mfma_f32_16x16x32_bf16 v[20:23], v[0:3], v[0:3], v[20:23]
	v_mfma_f32_16x16x32_bf16 v[12:15], v[0:3], v[0:3], v[12:15]
	v_mfma_f32_16x16x32_bf16 v[20:23], v[0:3], v[0:3], v[20:23]
	v_mfma_f32_16x16x32_bf16 v[12:15], v[0:3], v[0:3], v[12:15]
	v_mfma_f32_16x16x32_bf16 v[20:23], v[0:3], v[0:3], v[20:23]
	v_mfma_f32_16x16x32_bf16 v[12:15], v[0:3], v[0:3], v[12:15]
	v_mfma_f32_16x16x32_bf16 v[20:23], v[0:3], v[0:3], v[20:23]
	v_mfma_f32_16x16x32_bf16 v[24:27], v[0:3], v[0:3], v[12:15]
	v_mfma_f32_16x16x32_bf16 v[20:23], v[0:3], v[0:3], v[20:23]
	s_nop 4
	v_mov_b32_e32 v12, 0
	v_mov_b32_e32 v13, 0
	v_mov_b32_e32 v14, 0
	v_mfma_f32_16x16x32_bf16 v[24:27], v[0:3], v[0:3], v[24:27]
	v_mov_b32_e32 v15, 0
	ds_write_b128 v19, v[20:23]
	s_nop 5
	ds_write_b128 v19, v[24:27] offset:1024
	s_waitcnt lgkmcnt(0)
	s_barrier
	s_and_saveexec_b64 s[0:1], vcc
	s_cbranch_execz .LBB0_725
	ds_read_b128 v[12:15], v16
	ds_read_b128 v[20:23], v16 offset:2048
	ds_read_b128 v[24:27], v16 offset:4096
	ds_read_b128 v[28:31], v16 offset:6144
	s_waitcnt lgkmcnt(3)
	v_pk_add_f32 v[14:15], v[14:15], 0 op_sel_hi:[1,0]
	v_pk_add_f32 v[12:13], v[12:13], 0 op_sel_hi:[1,0]
	s_waitcnt lgkmcnt(2)
	v_pk_add_f32 v[14:15], v[14:15], v[22:23]
	v_pk_add_f32 v[20:21], v[12:13], v[20:21]
	s_waitcnt lgkmcnt(1)
	v_pk_add_f32 v[22:23], v[14:15], v[26:27]
	ds_read_b128 v[12:15], v16 offset:8192
	v_pk_add_f32 v[20:21], v[20:21], v[24:25]
	s_waitcnt lgkmcnt(1)
	v_pk_add_f32 v[24:25], v[22:23], v[30:31]
	v_pk_add_f32 v[28:29], v[20:21], v[28:29]
	ds_read_b128 v[20:23], v16 offset:10240
	s_waitcnt lgkmcnt(1)
	v_pk_add_f32 v[30:31], v[24:25], v[14:15]
	ds_read_b128 v[24:27], v16 offset:12288
	v_pk_add_f32 v[28:29], v[28:29], v[12:13]
	ds_read_b128 v[12:15], v16 offset:14336
	s_waitcnt lgkmcnt(2)
	v_pk_add_f32 v[22:23], v[30:31], v[22:23]
	v_pk_add_f32 v[20:21], v[28:29], v[20:21]
	s_waitcnt lgkmcnt(1)
	v_pk_add_f32 v[22:23], v[22:23], v[26:27]
	v_pk_add_f32 v[20:21], v[20:21], v[24:25]
	s_waitcnt lgkmcnt(0)
	v_pk_add_f32 v[14:15], v[22:23], v[14:15]
	v_pk_add_f32 v[12:13], v[20:21], v[12:13]

;     ...
;         for (int s0 = 0; s0 < nsw; s0 += KS) {
;             bf16x8 a[KS][NRB], b[KS], c[KS];
; #pragma unroll
;             for (int s = 0; s < KS; ++s) { const bool on = s0 + s < nsw; const int ko = (s0 + s) * 32;
;                 b[s] = on ? *(const bf16x8*)(bp + ko) : (bf16x8){0, 0, 0, 0, 0, 0, 0, 0}; if (TWO) c[s] = on ? *(const bf16x8*)(bp + (size_t)128 * K + ko) : (bf16x8){0, 0, 0, 0, 0, 0, 0, 0};
; #pragma unroll
;                 for (int r = 0; r < NRB; ++r) a[s][r] = on ? *(const bf16x8*)(ap + (size_t)(16 * r) * K + ko) : (bf16x8){0, 0, 0, 0, 0, 0, 0, 0}; }
; #pragma unroll
;             for (int s = 0; s < KS; ++s)
; #pragma unroll
;                 for (int r = 0; r < NRB; ++r) { acc0[r] = __builtin_amdgcn_mfma_f32_16x16x32_bf16(b[s], a[s][r], acc0[r], 0, 0, 0); if (TWO) acc1[r] = __builtin_amdgcn_mfma_f32_16x16x32_bf16(c[s], a[s][r], acc1[r], 0, 0, 0); }
;         }
;         f32x4 t0 = (f32x4){0.f, 0.f, 0.f, 0.f}, t1 = (f32x4){0.f, 0.f, 0.f, 0.f};
; #pragma unroll
;         for (int r = 0; r < NRB; ++r) red[(wave * NRB + r) * 64 + lane] = acc0[r];
;         __syncthreads();
;         if (wave < NRB) {
; #pragma unroll
;             for (int s = 0; s < 8; ++s) t0 += red[(s * NRB + wave) * 64 + lane]; }
.LBB0_729:
	s_ashr_i32 s0, s3, 31
	s_lshr_b32 s1, s0, 26
	s_add_i32 s1, s3, s1
	s_ashr_i32 s1, s1, 6
	s_lshr_b32 s5, s1, 30
	s_lshr_b32 s0, s0, 24
	s_add_i32 s5, s1, s5
	s_add_i32 s0, s3, s0
	s_and_b32 s5, s5, 0x7fffffc
	s_ashr_i32 s0, s0, 8
	s_sub_i32 s5, s1, s5
	s_lshl_b32 s0, s0, 7
	s_lshl_b32 s5, s5, 5
	s_lshl_b32 s6, s1, 10
	s_add_i32 s5, s0, s5
	s_sub_i32 s0, s10, s6
	v_add_u32_e32 v8, s0, v152
	v_ashrrev_i32_e32 v9, 31, v8
	v_lshlrev_b64 v[8:9], 11, v[8:9]
	s_addk_i32 s5, 0x4000
	v_lshl_add_u64 v[40:41], v[6:7], 0, v[8:9]
	v_or_b32_e32 v12, s5, v152
	v_ashrrev_i32_e32 v13, 31, v12
	v_lshlrev_b64 v[12:13], 11, v[12:13]
	v_lshl_add_u64 v[44:45], v[4:5], 0, v[12:13]
	v_add_co_u32_e64 v46, s[0:1], s4, v44
	s_nop 1
	v_addc_co_u32_e64 v47, s[0:1], 0, v45, s[0:1]
	global_load_dwordx4 v[48:51], v[40:41], off
	global_load_dwordx4 v[52:55], v[44:45], off
	global_load_dwordx4 v[56:59], v[46:47], off
	global_load_dwordx4 v[60:63], v[40:41], off offset:64
	global_load_dwordx4 v[64:67], v[44:45], off offset:64
	global_load_dwordx4 v[68:71], v[40:41], off offset:128
	global_load_dwordx4 v[72:75], v[46:47], off offset:64
	global_load_dwordx4 v[76:79], v[44:45], off offset:128
	global_load_dwordx4 v[80:83], v[40:41], off offset:192
	global_load_dwordx4 v[84:87], v[46:47], off offset:128
	global_load_dwordx4 v[88:91], v[44:45], off offset:192
	global_load_dwordx4 v[92:95], v[46:47], off offset:192
	s_waitcnt vmcnt(0)
	v_mfma_f32_16x16x32_bf16 v[12:15], v[48:51], v[52:55], 0
	v_mfma_f32_16x16x32_bf16 v[8:11], v[48:51], v[56:59], 0
	v_mfma_f32_16x16x32_bf16 v[12:15], v[60:63], v[64:67], v[12:15]
	v_mfma_f32_16x16x32_bf16 v[8:11], v[60:63], v[72:75], v[8:11]
	v_mfma_f32_16x16x32_bf16 v[12:15], v[68:71], v[76:79], v[12:15]
	v_mfma_f32_16x16x32_bf16 v[8:11], v[68:71], v[84:87], v[8:11]
	v_mfma_f32_16x16x32_bf16 v[12:15], v[80:83], v[88:91], v[12:15]
	v_mfma_f32_16x16x32_bf16 v[8:11], v[80:83], v[92:95], v[8:11]
	v_mfma_f32_16x16x32_bf16 v[12:15], v[0:3], v[0:3], v[12:15]
	v_mfma_f32_16x16x32_bf16 v[8:11], v[0:3], v[0:3], v[8:11]
	v_mfma_f32_16x16x32_bf16 v[12:15], v[0:3], v[0:3], v[12:15]
	v_mfma_f32_16x16x32_bf16 v[8:11], v[0:3], v[0:3], v[8:11]
	v_mfma_f32_16x16x32_bf16 v[12:15], v[0:3], v[0:3], v[12:15]
	v_mfma_f32_16x16x32_bf16 v[8:11], v[0:3], v[0:3], v[8:11]
	v_mfma_f32_16x16x32_bf16 v[12:15], v[0:3], v[0:3], v[12:15]
	v_mfma_f32_16x16x32_bf16 v[8:11], v[0:3], v[0:3], v[8:11]
	v_mfma_f32_16x16x32_bf16 v[12:15], v[0:3], v[0:3], v[12:15]
	v_mfma_f32_16x16x32_bf16 v[8:11], v[0:3], v[0:3], v[8:11]
	v_mfma_f32_16x16x32_bf16 v[12:15], v[0:3], v[0:3], v[12:15]
	v_mfma_f32_16x16x32_bf16 v[8:11], v[0:3], v[0:3], v[8:11]
	v_mfma_f32_16x16x32_bf16 v[12:15], v[0:3], v[0:3], v[12:15]
	v_mfma_f32_16x16x32_bf16 v[20:23], v[0:3], v[0:3], v[8:11]
	v_mfma_f32_16x16x32_bf16 v[12:15], v[0:3], v[0:3], v[12:15]
	s_nop 4
	v_mov_b32_e32 v8, 0
	v_mov_b32_e32 v9, 0
	v_mov_b32_e32 v10, 0
	v_mfma_f32_16x16x32_bf16 v[20:23], v[0:3], v[0:3], v[20:23]
	v_mov_b32_e32 v11, 0
	ds_write_b128 v19, v[12:15]
	s_nop 5
	ds_write_b128 v19, v[20:23] offset:1024
	s_waitcnt lgkmcnt(0)
	s_barrier
	s_and_saveexec_b64 s[0:1], vcc
	s_cbranch_execz .LBB0_731
	ds_read_b128 v[8:11], v16
	ds_read_b128 v[12:15], v16 offset:2048
	ds_read_b128 v[20:23], v16 offset:4096
	ds_read_b128 v[24:27], v16 offset:6144
	s_waitcnt lgkmcnt(3)
	v_pk_add_f32 v[10:11], v[10:11], 0 op_sel_hi:[1,0]
	v_pk_add_f32 v[8:9], v[8:9], 0 op_sel_hi:[1,0]
	s_waitcnt lgkmcnt(2)
	v_pk_add_f32 v[10:11], v[10:11], v[14:15]
	v_pk_add_f32 v[12:13], v[8:9], v[12:13]
	s_waitcnt lgkmcnt(1)
	v_pk_add_f32 v[14:15], v[10:11], v[22:23]
	ds_read_b128 v[8:11], v16 offset:8192
	v_pk_add_f32 v[12:13], v[12:13], v[20:21]
	s_waitcnt lgkmcnt(1)
	v_pk_add_f32 v[20:21], v[14:15], v[26:27]
	v_pk_add_f32 v[24:25], v[12:13], v[24:25]
	ds_read_b128 v[12:15], v16 offset:10240
	s_waitcnt lgkmcnt(1)
	v_pk_add_f32 v[26:27], v[20:21], v[10:11]
	ds_read_b128 v[20:23], v16 offset:12288
	v_pk_add_f32 v[24:25], v[24:25], v[8:9]
	ds_read_b128 v[8:11], v16 offset:14336
	s_waitcnt lgkmcnt(2)
	v_pk_add_f32 v[14:15], v[26:27], v[14:15]
	v_pk_add_f32 v[12:13], v[24:25], v[12:13]
	s_waitcnt lgkmcnt(1)
	v_pk_add_f32 v[14:15], v[14:15], v[22:23]
	v_pk_add_f32 v[12:13], v[12:13], v[20:21]
	s_waitcnt lgkmcnt(0)
	v_pk_add_f32 v[10:11], v[14:15], v[10:11]
	v_pk_add_f32 v[8:9], v[12:13], v[8:9]

;     ...
;         for (int s0 = 0; s0 < nsw; s0 += KS) {
;             bf16x8 a[KS][NRB], b[KS], c[KS];
; #pragma unroll
;             for (int s = 0; s < KS; ++s) { const bool on = s0 + s < nsw; const int ko = (s0 + s) * 32;
;                 b[s] = on ? *(const bf16x8*)(bp + ko) : (bf16x8){0, 0, 0, 0, 0, 0, 0, 0}; if (TWO) c[s] = on ? *(const bf16x8*)(bp + (size_t)128 * K + ko) : (bf16x8){0, 0, 0, 0, 0, 0, 0, 0};
; #pragma unroll
;                 for (int r = 0; r < NRB; ++r) a[s][r] = on ? *(const bf16x8*)(ap + (size_t)(16 * r) * K + ko) : (bf16x8){0, 0, 0, 0, 0, 0, 0, 0}; }
; #pragma unroll
;             for (int s = 0; s < KS; ++s)
; #pragma unroll
;                 for (int r = 0; r < NRB; ++r) { acc0[r] = __builtin_amdgcn_mfma_f32_16x16x32_bf16(b[s], a[s][r], acc0[r], 0, 0, 0); if (TWO) acc1[r] = __builtin_amdgcn_mfma_f32_16x16x32_bf16(c[s], a[s][r], acc1[r], 0, 0, 0); }
;         }
;         f32x4 t0 = (f32x4){0.f, 0.f, 0.f, 0.f}, t1 = (f32x4){0.f, 0.f, 0.f, 0.f};
; #pragma unroll
;         for (int r = 0; r < NRB; ++r) red[(wave * NRB + r) * 64 + lane] = acc0[r];
;         __syncthreads();
;         if (wave < NRB) {
; #pragma unroll
;             for (int s = 0; s < 8; ++s) t0 += red[(s * NRB + wave) * 64 + lane]; }
.LBB0_829:
	s_ashr_i32 s8, s3, 31
	s_lshr_b32 s9, s8, 26
	s_add_i32 s9, s3, s9
	s_ashr_i32 s10, s9, 6
	s_lshr_b32 s9, s10, 30
	s_lshr_b32 s8, s8, 24
	s_add_i32 s9, s10, s9
	s_add_i32 s8, s3, s8
	s_and_b32 s9, s9, 0x7fffffc
	s_ashr_i32 s8, s8, 8
	s_sub_i32 s9, s10, s9
	s_lshl_b32 s8, s8, 7
	s_lshl_b32 s9, s9, 5
	s_lshl_b32 s19, s10, 10
	s_add_i32 s11, s8, s9
	s_sub_i32 s8, s16, s19
	v_add_u32_e32 v8, s8, v148
	v_ashrrev_i32_e32 v9, 31, v8
	v_lshlrev_b64 v[8:9], 11, v[8:9]
	s_addk_i32 s11, 0x4000
	v_lshl_add_u64 v[44:45], v[6:7], 0, v[8:9]
	v_or_b32_e32 v12, s11, v148
	v_ashrrev_i32_e32 v13, 31, v12
	v_lshlrev_b64 v[12:13], 11, v[12:13]
	v_lshl_add_u64 v[12:13], v[4:5], 0, v[12:13]
	v_add_co_u32_e32 v48, vcc, s18, v12
	s_nop 1
	v_addc_co_u32_e32 v49, vcc, 0, v13, vcc
	global_load_dwordx4 v[52:55], v[44:45], off
	global_load_dwordx4 v[56:59], v[12:13], off
	global_load_dwordx4 v[60:63], v[48:49], off
	global_load_dwordx4 v[64:67], v[44:45], off offset:64
	global_load_dwordx4 v[68:71], v[12:13], off offset:64
	global_load_dwordx4 v[72:75], v[44:45], off offset:128
	global_load_dwordx4 v[76:79], v[48:49], off offset:64
	global_load_dwordx4 v[80:83], v[12:13], off offset:128
	global_load_dwordx4 v[84:87], v[44:45], off offset:192
	global_load_dwordx4 v[88:91], v[48:49], off offset:128
	global_load_dwordx4 v[92:95], v[12:13], off offset:192
	global_load_dwordx4 v[96:99], v[48:49], off offset:192
	s_waitcnt vmcnt(0)
	s_waitcnt lgkmcnt(0)
	v_mfma_f32_16x16x32_bf16 v[20:23], v[52:55], v[56:59], 0
	v_mfma_f32_16x16x32_bf16 v[8:11], v[52:55], v[60:63], 0
	v_mfma_f32_16x16x32_bf16 v[20:23], v[64:67], v[68:71], v[20:23]
	v_mfma_f32_16x16x32_bf16 v[8:11], v[64:67], v[76:79], v[8:11]
	v_mfma_f32_16x16x32_bf16 v[20:23], v[72:75], v[80:83], v[20:23]
	v_mfma_f32_16x16x32_bf16 v[8:11], v[72:75], v[88:91], v[8:11]
	v_mfma_f32_16x16x32_bf16 v[20:23], v[84:87], v[92:95], v[20:23]
	v_mfma_f32_16x16x32_bf16 v[8:11], v[84:87], v[96:99], v[8:11]
	v_mfma_f32_16x16x32_bf16 v[20:23], v[0:3], v[0:3], v[20:23]
	v_mfma_f32_16x16x32_bf16 v[8:11], v[0:3], v[0:3], v[8:11]
	v_mfma_f32_16x16x32_bf16 v[20:23], v[0:3], v[0:3], v[20:23]
	v_mfma_f32_16x16x32_bf16 v[8:11], v[0:3], v[0:3], v[8:11]
	v_mfma_f32_16x16x32_bf16 v[20:23], v[0:3], v[0:3], v[20:23]
	v_mfma_f32_16x16x32_bf16 v[8:11], v[0:3], v[0:3], v[8:11]
	v_mfma_f32_16x16x32_bf16 v[20:23], v[0:3], v[0:3], v[20:23]
	v_mfma_f32_16x16x32_bf16 v[8:11], v[0:3], v[0:3], v[8:11]
	v_mfma_f32_16x16x32_bf16 v[20:23], v[0:3], v[0:3], v[20:23]
	v_mfma_f32_16x16x32_bf16 v[8:11], v[0:3], v[0:3], v[8:11]
	v_mfma_f32_16x16x32_bf16 v[20:23], v[0:3], v[0:3], v[20:23]
	v_mfma_f32_16x16x32_bf16 v[8:11], v[0:3], v[0:3], v[8:11]
	v_mfma_f32_16x16x32_bf16 v[20:23], v[0:3], v[0:3], v[20:23]
	v_mfma_f32_16x16x32_bf16 v[24:27], v[0:3], v[0:3], v[8:11]
	v_mfma_f32_16x16x32_bf16 v[20:23], v[0:3], v[0:3], v[20:23]
	s_nop 4
	v_mov_b32_e32 v10, 0
	v_mov_b32_e32 v11, 0
	v_mov_b32_e32 v8, 0
	v_mfma_f32_16x16x32_bf16 v[24:27], v[0:3], v[0:3], v[24:27]
	v_mov_b32_e32 v9, 0
	ds_write_b128 v17, v[20:23]
	s_nop 5
	ds_write_b128 v17, v[24:27] offset:1024
	s_waitcnt lgkmcnt(0)
	s_barrier
	s_and_saveexec_b64 s[8:9], s[0:1]
	s_cbranch_execz .LBB0_831
	ds_read_b128 v[8:11], v14
	ds_read_b128 v[20:23], v14 offset:2048
	ds_read_b128 v[24:27], v14 offset:4096
	ds_read_b128 v[28:31], v14 offset:6144
	s_waitcnt lgkmcnt(3)
	v_pk_add_f32 v[10:11], v[10:11], 0 op_sel_hi:[1,0]
	v_pk_add_f32 v[8:9], v[8:9], 0 op_sel_hi:[1,0]
	s_waitcnt lgkmcnt(2)
	v_pk_add_f32 v[10:11], v[10:11], v[22:23]
	v_pk_add_f32 v[12:13], v[8:9], v[20:21]
	s_waitcnt lgkmcnt(1)
	v_pk_add_f32 v[20:21], v[10:11], v[26:27]
	ds_read_b128 v[8:11], v14 offset:8192
	v_pk_add_f32 v[12:13], v[12:13], v[24:25]
	s_waitcnt lgkmcnt(1)
	v_pk_add_f32 v[24:25], v[20:21], v[30:31]
	ds_read_b128 v[20:23], v14 offset:10240
	v_pk_add_f32 v[26:27], v[12:13], v[28:29]
	s_waitcnt lgkmcnt(1)
	v_pk_add_f32 v[28:29], v[24:25], v[10:11]
	ds_read_b128 v[10:13], v14 offset:12288
	v_pk_add_f32 v[8:9], v[26:27], v[8:9]
	ds_read_b128 v[24:27], v14 offset:14336
	s_waitcnt lgkmcnt(2)
	v_pk_add_f32 v[22:23], v[28:29], v[22:23]
	v_pk_add_f32 v[8:9], v[8:9], v[20:21]
	s_waitcnt lgkmcnt(1)
	v_pk_add_f32 v[12:13], v[22:23], v[12:13]
	v_pk_add_f32 v[10:11], v[8:9], v[10:11]
	s_waitcnt lgkmcnt(0)
	v_pk_add_f32 v[8:9], v[12:13], v[26:27]
	v_pk_add_f32 v[10:11], v[10:11], v[24:25]

;     ...
;         for (int s0 = 0; s0 < nsw; s0 += KS) {
;             bf16x8 a[KS][NRB], b[KS], c[KS];
; #pragma unroll
;             for (int s = 0; s < KS; ++s) { const bool on = s0 + s < nsw; const int ko = (s0 + s) * 32;
;                 b[s] = on ? *(const bf16x8*)(bp + ko) : (bf16x8){0, 0, 0, 0, 0, 0, 0, 0}; if (TWO) c[s] = on ? *(const bf16x8*)(bp + (size_t)128 * K + ko) : (bf16x8){0, 0, 0, 0, 0, 0, 0, 0};
; #pragma unroll
;                 for (int r = 0; r < NRB; ++r) a[s][r] = on ? *(const bf16x8*)(ap + (size_t)(16 * r) * K + ko) : (bf16x8){0, 0, 0, 0, 0, 0, 0, 0}; }
; #pragma unroll
;             for (int s = 0; s < KS; ++s)
; #pragma unroll
;                 for (int r = 0; r < NRB; ++r) { acc0[r] = __builtin_amdgcn_mfma_f32_16x16x32_bf16(b[s], a[s][r], acc0[r], 0, 0, 0); if (TWO) acc1[r] = __builtin_amdgcn_mfma_f32_16x16x32_bf16(c[s], a[s][r], acc1[r], 0, 0, 0); }
;         }
;         f32x4 t0 = (f32x4){0.f, 0.f, 0.f, 0.f}, t1 = (f32x4){0.f, 0.f, 0.f, 0.f};
; #pragma unroll
;         for (int r = 0; r < NRB; ++r) red[(wave * NRB + r) * 64 + lane] = acc0[r];
;         __syncthreads();
;         if (wave < NRB) {
; #pragma unroll
;             for (int s = 0; s < 8; ++s) t0 += red[(s * NRB + wave) * 64 + lane]; }
.LBB0_1295:
	s_ashr_i32 s6, s3, 31
	s_lshr_b32 s7, s6, 26
	s_add_i32 s7, s3, s7
	s_ashr_i32 s17, s7, 6
	s_lshr_b32 s7, s17, 30
	s_lshr_b32 s6, s6, 24
	s_add_i32 s7, s17, s7
	s_add_i32 s6, s3, s6
	s_and_b32 s7, s7, 0x7fffffc
	s_ashr_i32 s6, s6, 8
	s_sub_i32 s7, s17, s7
	s_lshl_b32 s6, s6, 7
	s_lshl_b32 s7, s7, 5
	s_lshl_b32 s19, s17, 10
	s_add_i32 s18, s6, s7
	s_sub_i32 s6, s10, s19
	v_add_u32_e32 v8, s6, v150
	v_ashrrev_i32_e32 v9, 31, v8
	v_lshlrev_b64 v[8:9], 11, v[8:9]
	s_addk_i32 s18, 0x4000
	v_lshl_add_u64 v[48:49], v[6:7], 0, v[8:9]
	v_or_b32_e32 v12, s18, v150
	s_waitcnt lgkmcnt(0)
	v_ashrrev_i32_e32 v13, 31, v12
	v_lshlrev_b64 v[12:13], 11, v[12:13]
	v_lshl_add_u64 v[12:13], v[4:5], 0, v[12:13]
	v_add_co_u32_e32 v50, vcc, s16, v12
	s_nop 1
	v_addc_co_u32_e32 v51, vcc, 0, v13, vcc
	global_load_dwordx4 v[52:55], v[48:49], off
	global_load_dwordx4 v[56:59], v[12:13], off
	global_load_dwordx4 v[60:63], v[50:51], off
	global_load_dwordx4 v[64:67], v[48:49], off offset:64
	global_load_dwordx4 v[68:71], v[12:13], off offset:64
	global_load_dwordx4 v[72:75], v[48:49], off offset:128
	global_load_dwordx4 v[76:79], v[50:51], off offset:64
	global_load_dwordx4 v[80:83], v[12:13], off offset:128
	global_load_dwordx4 v[84:87], v[48:49], off offset:192
	global_load_dwordx4 v[88:91], v[50:51], off offset:128
	global_load_dwordx4 v[92:95], v[12:13], off offset:192
	global_load_dwordx4 v[96:99], v[50:51], off offset:192
	s_waitcnt vmcnt(0)
	v_mfma_f32_16x16x32_bf16 v[20:23], v[52:55], v[56:59], 0
	v_mfma_f32_16x16x32_bf16 v[8:11], v[52:55], v[60:63], 0
	v_mfma_f32_16x16x32_bf16 v[20:23], v[64:67], v[68:71], v[20:23]
	v_mfma_f32_16x16x32_bf16 v[8:11], v[64:67], v[76:79], v[8:11]
	v_mov_b32_e32 v12, 0
	v_mov_b32_e32 v13, 0
	v_mfma_f32_16x16x32_bf16 v[20:23], v[72:75], v[80:83], v[20:23]
	v_mfma_f32_16x16x32_bf16 v[8:11], v[72:75], v[88:91], v[8:11]
	v_mfma_f32_16x16x32_bf16 v[20:23], v[84:87], v[92:95], v[20:23]
	v_mfma_f32_16x16x32_bf16 v[8:11], v[84:87], v[96:99], v[8:11]
	v_mfma_f32_16x16x32_bf16 v[20:23], v[0:3], v[0:3], v[20:23]
	v_mfma_f32_16x16x32_bf16 v[8:11], v[0:3], v[0:3], v[8:11]
	v_mfma_f32_16x16x32_bf16 v[20:23], v[0:3], v[0:3], v[20:23]
	v_mfma_f32_16x16x32_bf16 v[8:11], v[0:3], v[0:3], v[8:11]
	v_mfma_f32_16x16x32_bf16 v[20:23], v[0:3], v[0:3], v[20:23]
	v_mfma_f32_16x16x32_bf16 v[8:11], v[0:3], v[0:3], v[8:11]
	v_mfma_f32_16x16x32_bf16 v[20:23], v[0:3], v[0:3], v[20:23]
	v_mfma_f32_16x16x32_bf16 v[8:11], v[0:3], v[0:3], v[8:11]
	v_mfma_f32_16x16x32_bf16 v[20:23], v[0:3], v[0:3], v[20:23]
	v_mfma_f32_16x16x32_bf16 v[8:11], v[0:3], v[0:3], v[8:11]
	v_mfma_f32_16x16x32_bf16 v[20:23], v[0:3], v[0:3], v[20:23]
	v_mfma_f32_16x16x32_bf16 v[8:11], v[0:3], v[0:3], v[8:11]
	v_mfma_f32_16x16x32_bf16 v[20:23], v[0:3], v[0:3], v[20:23]
	v_mfma_f32_16x16x32_bf16 v[24:27], v[0:3], v[0:3], v[8:11]
	v_mfma_f32_16x16x32_bf16 v[20:23], v[0:3], v[0:3], v[20:23]
	s_nop 4
	v_mov_b32_e32 v10, 0
	v_mov_b32_e32 v11, 0
	v_mfma_f32_16x16x32_bf16 v[24:27], v[0:3], v[0:3], v[24:27]
	ds_write_b128 v19, v[20:23]
	s_nop 6
	ds_write_b128 v19, v[24:27] offset:1024
	s_waitcnt lgkmcnt(0)
	s_barrier
	s_and_saveexec_b64 s[6:7], s[0:1]
	s_cbranch_execz .LBB0_1297
	ds_read_b128 v[8:11], v16
	ds_read_b128 v[20:23], v16 offset:2048
	ds_read_b128 v[24:27], v16 offset:4096
	ds_read_b128 v[28:31], v16 offset:6144
	s_waitcnt lgkmcnt(3)
	v_pk_add_f32 v[10:11], v[10:11], 0 op_sel_hi:[1,0]
	v_pk_add_f32 v[8:9], v[8:9], 0 op_sel_hi:[1,0]
	s_waitcnt lgkmcnt(2)
	v_pk_add_f32 v[10:11], v[10:11], v[22:23]
	v_pk_add_f32 v[12:13], v[8:9], v[20:21]
	s_waitcnt lgkmcnt(1)
	v_pk_add_f32 v[20:21], v[10:11], v[26:27]
	ds_read_b128 v[8:11], v16 offset:8192
	v_pk_add_f32 v[12:13], v[12:13], v[24:25]
	s_waitcnt lgkmcnt(1)
	v_pk_add_f32 v[24:25], v[20:21], v[30:31]
	ds_read_b128 v[20:23], v16 offset:10240
	v_pk_add_f32 v[26:27], v[12:13], v[28:29]
	s_waitcnt lgkmcnt(1)
	v_pk_add_f32 v[28:29], v[24:25], v[10:11]
	ds_read_b128 v[10:13], v16 offset:12288
	v_pk_add_f32 v[8:9], v[26:27], v[8:9]
	ds_read_b128 v[24:27], v16 offset:14336
	s_waitcnt lgkmcnt(2)
	v_pk_add_f32 v[22:23], v[28:29], v[22:23]
	v_pk_add_f32 v[8:9], v[8:9], v[20:21]
	s_waitcnt lgkmcnt(1)
	v_pk_add_f32 v[12:13], v[22:23], v[12:13]
	v_pk_add_f32 v[8:9], v[8:9], v[10:11]
	s_waitcnt lgkmcnt(0)
	v_pk_add_f32 v[10:11], v[12:13], v[26:27]
	v_pk_add_f32 v[12:13], v[8:9], v[24:25]
